# in-proj epilogue: 75 adjacent (1+e) add pairs packed into v_pk_add_f32
# speedup vs baseline: 1.0001x; 1.0001x over previous
.LBB0_408:
	s_cmp_gt_u32 s18, 8
	s_cbranch_scc0 .LBB0_414
	s_cmp_lt_i32 s18, 10
	s_cbranch_scc1 .LBB0_478
	s_mov_b64 s[38:39], -1
	s_cmp_lg_u32 s18, 10
	s_cbranch_scc0 .LBB0_412
	s_add_i32 s5, s18, -11
	v_mul_f32_e32 v130, 0xbfb8aa3b, v124
	v_mul_f32_e32 v131, 0xbfb8aa3b, v125
	v_mul_f32_e32 v132, 0xbfb8aa3b, v126
	v_mul_f32_e32 v133, 0xbfb8aa3b, v127
	v_mul_f32_e32 v134, 0xbfb8aa3b, v120
	v_mul_f32_e32 v135, 0xbfb8aa3b, v121
	s_lshr_b32 s10, s5, 2
	v_exp_f32_e32 v130, v130
	v_exp_f32_e32 v131, v131
	v_exp_f32_e32 v132, v132
	v_exp_f32_e32 v133, v133
	v_exp_f32_e32 v134, v134
	v_exp_f32_e32 v135, v135
	s_mul_i32 s10, s10, 48
	s_add_i32 s10, s10, s68
	s_ashr_i32 s11, s10, 31
	v_mul_f32_e32 v136, 0xbfb8aa3b, v122
	v_mul_f32_e32 v137, 0xbfb8aa3b, v123
	s_lshl_b64 s[10:11], s[10:11], 19
	v_readlane_b32 s16, v255, 50
	v_pk_add_f32 v[130:131], v[130:131], 1.0 op_sel_hi:[1,0]
	s_nop 0
	v_pk_add_f32 v[132:133], v[132:133], 1.0 op_sel_hi:[1,0]
	s_nop 0
	v_pk_add_f32 v[134:135], v[134:135], 1.0 op_sel_hi:[1,0]
	s_nop 0
	v_exp_f32_e32 v136, v136
	v_exp_f32_e32 v137, v137
	s_add_u32 s10, s16, s10
	v_readlane_b32 s16, v255, 51
	v_rcp_f32_e32 v130, v130
	v_rcp_f32_e32 v131, v131
	v_rcp_f32_e32 v132, v132
	v_rcp_f32_e32 v133, v133
	v_rcp_f32_e32 v134, v134
	v_rcp_f32_e32 v135, v135
	s_addc_u32 s11, s16, s11
	s_lshl_b32 s5, s5, 17
	s_and_b32 s5, s5, 0x60000
	s_add_u32 s10, s10, s5
	v_pk_add_f32 v[136:137], v[136:137], 1.0 op_sel_hi:[1,0]
	s_nop 0
	s_addc_u32 s11, s11, 0
	s_lshl_b32 s5, s82, 10
	s_lshl_b32 s16, s97, 12
	v_rcp_f32_e32 v136, v136
	v_rcp_f32_e32 v137, v137
	v_cvt_pk_bf16_f32 v130, v130, v131
	v_cvt_pk_bf16_f32 v131, v132, v133
	v_cvt_pk_bf16_f32 v132, v134, v135
	v_mul_f32_e32 v134, 0xbfb8aa3b, v116
	v_mul_f32_e32 v135, 0xbfb8aa3b, v117
	v_lshlrev_b32_e32 v128, 4, v159
	s_add_i32 s16, s16, s5
	v_exp_f32_e32 v134, v134
	v_exp_f32_e32 v135, v135
	v_add3_u32 v128, s16, v157, v128
	v_ashrrev_i32_e32 v129, 31, v128
	v_lshl_add_u64 v[128:129], v[128:129], 4, s[10:11]
	v_cvt_pk_bf16_f32 v133, v136, v137
	global_store_dwordx4 v[128:129], v[130:133], off
	v_mul_f32_e32 v136, 0xbfb8aa3b, v114
	v_mul_f32_e32 v137, 0xbfb8aa3b, v115
	v_add_f32_e32 v130, 1.0, v134
	v_add_f32_e32 v131, 1.0, v135
	v_mul_f32_e32 v132, 0xbfb8aa3b, v118
	v_mul_f32_e32 v133, 0xbfb8aa3b, v119
	v_mul_f32_e32 v134, 0xbfb8aa3b, v112
	v_mul_f32_e32 v135, 0xbfb8aa3b, v113
	v_exp_f32_e32 v132, v132
	v_exp_f32_e32 v133, v133
	v_exp_f32_e32 v134, v134
	v_exp_f32_e32 v135, v135
	v_pk_add_f32 v[132:133], v[132:133], 1.0 op_sel_hi:[1,0]
	s_nop 0
	v_pk_add_f32 v[134:135], v[134:135], 1.0 op_sel_hi:[1,0]
	s_nop 0
	v_exp_f32_e32 v136, v136
	v_exp_f32_e32 v137, v137
	v_rcp_f32_e32 v130, v130
	v_rcp_f32_e32 v131, v131
	v_rcp_f32_e32 v132, v132
	v_rcp_f32_e32 v133, v133
	v_rcp_f32_e32 v134, v134
	v_rcp_f32_e32 v135, v135
	v_pk_add_f32 v[136:137], v[136:137], 1.0 op_sel_hi:[1,0]
	s_nop 0
	v_rcp_f32_e32 v136, v136
	v_rcp_f32_e32 v137, v137
	v_cvt_pk_bf16_f32 v130, v130, v131
	v_cvt_pk_bf16_f32 v131, v132, v133
	v_cvt_pk_bf16_f32 v132, v134, v135
	v_mul_f32_e32 v134, 0xbfb8aa3b, v108
	v_mul_f32_e32 v135, 0xbfb8aa3b, v109
	v_exp_f32_e32 v134, v134
	v_exp_f32_e32 v135, v135
	v_cvt_pk_bf16_f32 v133, v136, v137
	global_store_dwordx4 v[128:129], v[130:133], off offset:1024
	v_mul_f32_e32 v136, 0xbfb8aa3b, v106
	v_mul_f32_e32 v137, 0xbfb8aa3b, v107
	v_add_f32_e32 v130, 1.0, v134
	v_add_f32_e32 v131, 1.0, v135
	v_mul_f32_e32 v132, 0xbfb8aa3b, v110
	v_mul_f32_e32 v133, 0xbfb8aa3b, v111
	v_mul_f32_e32 v134, 0xbfb8aa3b, v104
	v_mul_f32_e32 v135, 0xbfb8aa3b, v105
	v_exp_f32_e32 v132, v132
	v_exp_f32_e32 v133, v133
	v_exp_f32_e32 v134, v134
	v_exp_f32_e32 v135, v135
	v_pk_add_f32 v[132:133], v[132:133], 1.0 op_sel_hi:[1,0]
	s_nop 0
	v_pk_add_f32 v[134:135], v[134:135], 1.0 op_sel_hi:[1,0]
	s_nop 0
	v_exp_f32_e32 v136, v136
	v_exp_f32_e32 v137, v137
	v_rcp_f32_e32 v130, v130
	v_rcp_f32_e32 v131, v131
	v_rcp_f32_e32 v132, v132
	v_rcp_f32_e32 v133, v133
	v_rcp_f32_e32 v134, v134
	v_rcp_f32_e32 v135, v135
	v_pk_add_f32 v[136:137], v[136:137], 1.0 op_sel_hi:[1,0]
	s_nop 0
	v_rcp_f32_e32 v136, v136
	v_rcp_f32_e32 v137, v137
	v_cvt_pk_bf16_f32 v130, v130, v131
	v_cvt_pk_bf16_f32 v131, v132, v133
	v_cvt_pk_bf16_f32 v132, v134, v135
	v_mul_f32_e32 v134, 0xbfb8aa3b, v100
	v_mul_f32_e32 v135, 0xbfb8aa3b, v101
	v_exp_f32_e32 v134, v134
	v_exp_f32_e32 v135, v135
	v_cvt_pk_bf16_f32 v133, v136, v137
	global_store_dwordx4 v[128:129], v[130:133], off offset:2048
	v_mul_f32_e32 v136, 0xbfb8aa3b, v98
	v_mul_f32_e32 v137, 0xbfb8aa3b, v99
	v_add_f32_e32 v130, 1.0, v134
	v_add_f32_e32 v131, 1.0, v135
	v_mul_f32_e32 v132, 0xbfb8aa3b, v102
	v_mul_f32_e32 v133, 0xbfb8aa3b, v103
	v_mul_f32_e32 v134, 0xbfb8aa3b, v96
	v_mul_f32_e32 v135, 0xbfb8aa3b, v97
	v_exp_f32_e32 v132, v132
	v_exp_f32_e32 v133, v133
	v_exp_f32_e32 v134, v134
	v_exp_f32_e32 v135, v135
	v_exp_f32_e32 v136, v136
	v_exp_f32_e32 v137, v137
	v_pk_add_f32 v[132:133], v[132:133], 1.0 op_sel_hi:[1,0]
	s_nop 0
	v_pk_add_f32 v[134:135], v[134:135], 1.0 op_sel_hi:[1,0]
	s_nop 0
	v_pk_add_f32 v[136:137], v[136:137], 1.0 op_sel_hi:[1,0]
	s_nop 0
	v_rcp_f32_e32 v130, v130
	v_rcp_f32_e32 v131, v131
	v_rcp_f32_e32 v132, v132
	v_rcp_f32_e32 v133, v133
	v_rcp_f32_e32 v134, v134
	v_rcp_f32_e32 v135, v135
	v_rcp_f32_e32 v136, v136
	v_rcp_f32_e32 v137, v137
	v_cvt_pk_bf16_f32 v130, v130, v131
	v_cvt_pk_bf16_f32 v131, v132, v133
	v_cvt_pk_bf16_f32 v132, v134, v135
	v_cvt_pk_bf16_f32 v133, v136, v137
	global_store_dwordx4 v[128:129], v[130:133], off offset:3072
	v_mul_f32_e32 v134, 0xbfb8aa3b, v92
	v_exp_f32_e32 v134, v134
	v_mul_f32_e32 v132, 0xbfb8aa3b, v94
	v_exp_f32_e32 v132, v132
	v_mul_f32_e32 v133, 0xbfb8aa3b, v95
	v_mul_f32_e32 v135, 0xbfb8aa3b, v93
	v_exp_f32_e32 v133, v133
	v_exp_f32_e32 v135, v135
	v_add_f32_e32 v132, 1.0, v132
	v_add_f32_e32 v130, 1.0, v134
	v_rcp_f32_e32 v134, v132
	v_add_f32_e32 v132, 1.0, v133
	v_mul_f32_e32 v133, 0xbfb8aa3b, v88
	v_add_f32_e32 v131, 1.0, v135
	v_exp_f32_e32 v133, v133
	v_mul_f32_e32 v135, 0xbfb8aa3b, v89
	v_exp_f32_e32 v135, v135
	v_rcp_f32_e32 v136, v132
	v_add_f32_e32 v132, 1.0, v133
	v_mul_f32_e32 v133, 0xbfb8aa3b, v90
	v_rcp_f32_e32 v137, v132
	v_add_f32_e32 v132, 1.0, v135
	v_exp_f32_e32 v133, v133
	v_mul_f32_e32 v135, 0xbfb8aa3b, v91
	v_exp_f32_e32 v135, v135
	v_rcp_f32_e32 v138, v132
	v_add_f32_e32 v132, 1.0, v133
	v_rcp_f32_e32 v139, v132
	v_add_f32_e32 v132, 1.0, v135
	v_rcp_f32_e32 v135, v132
	v_rcp_f32_e32 v130, v130
	v_rcp_f32_e32 v131, v131
	v_cvt_pk_bf16_f32 v133, v134, v136
	v_cvt_pk_bf16_f32 v134, v137, v138
	v_cvt_pk_bf16_f32 v135, v139, v135
	v_mul_f32_e32 v138, 0xbfb8aa3b, v84
	v_mul_f32_e32 v139, 0xbfb8aa3b, v85
	v_add_co_u32_e32 v136, vcc, s33, v128
	v_exp_f32_e32 v138, v138
	v_exp_f32_e32 v139, v139
	v_addc_co_u32_e32 v137, vcc, 0, v129, vcc
	v_cvt_pk_bf16_f32 v132, v130, v131
	v_add_co_u32_e32 v130, vcc, s35, v128
	v_mul_f32_e32 v140, 0xbfb8aa3b, v82
	s_nop 0
	v_addc_co_u32_e32 v131, vcc, 0, v129, vcc
	global_store_dwordx4 v[130:131], v[132:135], off offset:-4096
	v_mul_f32_e32 v141, 0xbfb8aa3b, v83
	v_exp_f32_e32 v140, v140
	v_add_f32_e32 v132, 1.0, v138
	v_add_f32_e32 v133, 1.0, v139
	v_mul_f32_e32 v134, 0xbfb8aa3b, v86
	v_mul_f32_e32 v135, 0xbfb8aa3b, v87
	v_mul_f32_e32 v138, 0xbfb8aa3b, v80
	v_mul_f32_e32 v139, 0xbfb8aa3b, v81
	v_exp_f32_e32 v134, v134
	v_exp_f32_e32 v135, v135
	v_exp_f32_e32 v138, v138
	v_exp_f32_e32 v139, v139
	v_pk_add_f32 v[134:135], v[134:135], 1.0 op_sel_hi:[1,0]
	s_nop 0
	v_pk_add_f32 v[138:139], v[138:139], 1.0 op_sel_hi:[1,0]
	s_nop 0
	v_exp_f32_e32 v141, v141
	v_rcp_f32_e32 v132, v132
	v_rcp_f32_e32 v133, v133
	v_rcp_f32_e32 v134, v134
	v_rcp_f32_e32 v135, v135
	v_rcp_f32_e32 v138, v138
	v_rcp_f32_e32 v139, v139
	v_pk_add_f32 v[140:141], v[140:141], 1.0 op_sel_hi:[1,0]
	s_nop 0
	v_rcp_f32_e32 v140, v140
	v_rcp_f32_e32 v141, v141
	v_cvt_pk_bf16_f32 v132, v132, v133
	v_cvt_pk_bf16_f32 v133, v134, v135
	v_cvt_pk_bf16_f32 v134, v138, v139
	v_mul_f32_e32 v138, 0xbfb8aa3b, v76
	v_mul_f32_e32 v139, 0xbfb8aa3b, v77
	v_exp_f32_e32 v138, v138
	v_exp_f32_e32 v139, v139
	v_cvt_pk_bf16_f32 v135, v140, v141
	global_store_dwordx4 v[136:137], v[132:135], off offset:1024
	v_mul_f32_e32 v140, 0xbfb8aa3b, v74
	v_mul_f32_e32 v141, 0xbfb8aa3b, v75
	v_add_f32_e32 v132, 1.0, v138
	v_add_f32_e32 v133, 1.0, v139
	v_mul_f32_e32 v134, 0xbfb8aa3b, v78
	v_mul_f32_e32 v135, 0xbfb8aa3b, v79
	v_mul_f32_e32 v138, 0xbfb8aa3b, v72
	v_mul_f32_e32 v139, 0xbfb8aa3b, v73
	v_exp_f32_e32 v134, v134
	v_exp_f32_e32 v135, v135
	v_exp_f32_e32 v138, v138
	v_exp_f32_e32 v139, v139
	v_pk_add_f32 v[134:135], v[134:135], 1.0 op_sel_hi:[1,0]
	s_nop 0
	v_pk_add_f32 v[138:139], v[138:139], 1.0 op_sel_hi:[1,0]
	s_nop 0
	v_exp_f32_e32 v140, v140
	v_exp_f32_e32 v141, v141
	v_rcp_f32_e32 v132, v132
	v_rcp_f32_e32 v133, v133
	v_rcp_f32_e32 v134, v134
	v_rcp_f32_e32 v135, v135
	v_rcp_f32_e32 v138, v138
	v_rcp_f32_e32 v139, v139
	v_pk_add_f32 v[140:141], v[140:141], 1.0 op_sel_hi:[1,0]
	s_nop 0
	v_rcp_f32_e32 v140, v140
	v_rcp_f32_e32 v141, v141
	v_cvt_pk_bf16_f32 v132, v132, v133
	v_cvt_pk_bf16_f32 v133, v134, v135
	v_cvt_pk_bf16_f32 v134, v138, v139
	v_mul_f32_e32 v138, 0xbfb8aa3b, v68
	v_mul_f32_e32 v139, 0xbfb8aa3b, v69
	v_exp_f32_e32 v138, v138
	v_exp_f32_e32 v139, v139
	v_cvt_pk_bf16_f32 v135, v140, v141
	global_store_dwordx4 v[136:137], v[132:135], off offset:2048
	v_mul_f32_e32 v140, 0xbfb8aa3b, v66
	v_mul_f32_e32 v141, 0xbfb8aa3b, v67
	v_add_f32_e32 v132, 1.0, v138
	v_add_f32_e32 v133, 1.0, v139
	v_mul_f32_e32 v134, 0xbfb8aa3b, v70
	v_mul_f32_e32 v135, 0xbfb8aa3b, v71
	v_mul_f32_e32 v138, 0xbfb8aa3b, v64
	v_mul_f32_e32 v139, 0xbfb8aa3b, v65
	v_exp_f32_e32 v134, v134
	v_exp_f32_e32 v135, v135
	v_exp_f32_e32 v138, v138
	v_exp_f32_e32 v139, v139
	v_exp_f32_e32 v140, v140
	v_exp_f32_e32 v141, v141
	v_pk_add_f32 v[134:135], v[134:135], 1.0 op_sel_hi:[1,0]
	s_nop 0
	v_pk_add_f32 v[138:139], v[138:139], 1.0 op_sel_hi:[1,0]
	s_nop 0
	v_pk_add_f32 v[140:141], v[140:141], 1.0 op_sel_hi:[1,0]
	s_nop 0
	v_rcp_f32_e32 v132, v132
	v_rcp_f32_e32 v133, v133
	v_rcp_f32_e32 v134, v134
	v_rcp_f32_e32 v135, v135
	v_rcp_f32_e32 v138, v138
	v_rcp_f32_e32 v139, v139
	v_rcp_f32_e32 v140, v140
	v_rcp_f32_e32 v141, v141
	v_cvt_pk_bf16_f32 v132, v132, v133
	v_cvt_pk_bf16_f32 v133, v134, v135
	v_cvt_pk_bf16_f32 v134, v138, v139
	v_cvt_pk_bf16_f32 v135, v140, v141
	v_mul_f32_e32 v138, 0xbfb8aa3b, v60
	v_mul_f32_e32 v139, 0xbfb8aa3b, v61
	v_exp_f32_e32 v138, v138
	v_exp_f32_e32 v139, v139
	global_store_dwordx4 v[136:137], v[132:135], off offset:3072
	v_mul_f32_e32 v136, 0xbfb8aa3b, v56
	v_mul_f32_e32 v137, 0xbfb8aa3b, v57
	v_mul_f32_e32 v134, 0xbfb8aa3b, v62
	v_mul_f32_e32 v135, 0xbfb8aa3b, v63
	v_exp_f32_e32 v134, v134
	v_exp_f32_e32 v135, v135
	v_exp_f32_e32 v136, v136
	v_exp_f32_e32 v137, v137
	v_add_f32_e32 v132, 1.0, v138
	v_add_f32_e32 v133, 1.0, v139
	v_mul_f32_e32 v138, 0xbfb8aa3b, v58
	v_mul_f32_e32 v139, 0xbfb8aa3b, v59
	v_pk_add_f32 v[134:135], v[134:135], 1.0 op_sel_hi:[1,0]
	s_nop 0
	v_pk_add_f32 v[136:137], v[136:137], 1.0 op_sel_hi:[1,0]
	s_nop 0
	v_exp_f32_e32 v138, v138
	v_exp_f32_e32 v139, v139
	v_rcp_f32_e32 v132, v132
	v_rcp_f32_e32 v133, v133
	v_rcp_f32_e32 v134, v134
	v_rcp_f32_e32 v135, v135
	v_rcp_f32_e32 v136, v136
	v_rcp_f32_e32 v137, v137
	v_pk_add_f32 v[138:139], v[138:139], 1.0 op_sel_hi:[1,0]
	s_nop 0
	v_rcp_f32_e32 v138, v138
	v_rcp_f32_e32 v139, v139
	v_cvt_pk_bf16_f32 v132, v132, v133
	v_cvt_pk_bf16_f32 v133, v134, v135
	v_cvt_pk_bf16_f32 v134, v136, v137
	v_mul_f32_e32 v136, 0xbfb8aa3b, v52
	v_mul_f32_e32 v137, 0xbfb8aa3b, v53
	v_exp_f32_e32 v136, v136
	v_exp_f32_e32 v137, v137
	v_cvt_pk_bf16_f32 v135, v138, v139
	global_store_dwordx4 v[130:131], v[132:135], off
	v_mul_f32_e32 v138, 0xbfb8aa3b, v50
	v_mul_f32_e32 v139, 0xbfb8aa3b, v51
	v_add_f32_e32 v132, 1.0, v136
	v_add_f32_e32 v133, 1.0, v137
	v_mul_f32_e32 v134, 0xbfb8aa3b, v54
	v_mul_f32_e32 v135, 0xbfb8aa3b, v55
	v_mul_f32_e32 v136, 0xbfb8aa3b, v48
	v_mul_f32_e32 v137, 0xbfb8aa3b, v49
	v_exp_f32_e32 v134, v134
	v_exp_f32_e32 v135, v135
	v_exp_f32_e32 v136, v136
	v_exp_f32_e32 v137, v137
	v_pk_add_f32 v[134:135], v[134:135], 1.0 op_sel_hi:[1,0]
	s_nop 0
	v_pk_add_f32 v[136:137], v[136:137], 1.0 op_sel_hi:[1,0]
	s_nop 0
	v_exp_f32_e32 v138, v138
	v_exp_f32_e32 v139, v139
	v_rcp_f32_e32 v132, v132
	v_rcp_f32_e32 v133, v133
	v_rcp_f32_e32 v134, v134
	v_rcp_f32_e32 v135, v135
	v_rcp_f32_e32 v136, v136
	v_rcp_f32_e32 v137, v137
	v_pk_add_f32 v[138:139], v[138:139], 1.0 op_sel_hi:[1,0]
	s_nop 0
	v_rcp_f32_e32 v138, v138
	v_rcp_f32_e32 v139, v139
	v_cvt_pk_bf16_f32 v132, v132, v133
	v_cvt_pk_bf16_f32 v133, v134, v135
	v_cvt_pk_bf16_f32 v134, v136, v137
	v_mul_f32_e32 v136, 0xbfb8aa3b, v44
	v_mul_f32_e32 v137, 0xbfb8aa3b, v45
	v_exp_f32_e32 v136, v136
	v_exp_f32_e32 v137, v137
	v_cvt_pk_bf16_f32 v135, v138, v139
	global_store_dwordx4 v[130:131], v[132:135], off offset:1024
	v_mul_f32_e32 v138, 0xbfb8aa3b, v42
	v_mul_f32_e32 v139, 0xbfb8aa3b, v43
	v_add_f32_e32 v132, 1.0, v136
	v_add_f32_e32 v133, 1.0, v137
	v_mul_f32_e32 v134, 0xbfb8aa3b, v46
	v_mul_f32_e32 v135, 0xbfb8aa3b, v47
	v_mul_f32_e32 v136, 0xbfb8aa3b, v40
	v_mul_f32_e32 v137, 0xbfb8aa3b, v41
	v_exp_f32_e32 v134, v134
	v_exp_f32_e32 v135, v135
	v_exp_f32_e32 v136, v136
	v_exp_f32_e32 v137, v137
	v_pk_add_f32 v[134:135], v[134:135], 1.0 op_sel_hi:[1,0]
	s_nop 0
	v_pk_add_f32 v[136:137], v[136:137], 1.0 op_sel_hi:[1,0]
	s_nop 0
	v_exp_f32_e32 v138, v138
	v_exp_f32_e32 v139, v139
	v_rcp_f32_e32 v132, v132
	v_rcp_f32_e32 v133, v133
	v_rcp_f32_e32 v134, v134
	v_rcp_f32_e32 v135, v135
	v_rcp_f32_e32 v136, v136
	v_rcp_f32_e32 v137, v137
	v_pk_add_f32 v[138:139], v[138:139], 1.0 op_sel_hi:[1,0]
	s_nop 0
	v_rcp_f32_e32 v138, v138
	v_rcp_f32_e32 v139, v139
	v_cvt_pk_bf16_f32 v132, v132, v133
	v_cvt_pk_bf16_f32 v133, v134, v135
	v_cvt_pk_bf16_f32 v134, v136, v137
	v_mul_f32_e32 v136, 0xbfb8aa3b, v36
	v_mul_f32_e32 v137, 0xbfb8aa3b, v37
	v_exp_f32_e32 v136, v136
	v_exp_f32_e32 v137, v137
	v_cvt_pk_bf16_f32 v135, v138, v139
	global_store_dwordx4 v[130:131], v[132:135], off offset:2048
	v_mul_f32_e32 v138, 0xbfb8aa3b, v34
	v_mul_f32_e32 v139, 0xbfb8aa3b, v35
	v_add_f32_e32 v132, 1.0, v136
	v_add_f32_e32 v133, 1.0, v137
	v_mul_f32_e32 v134, 0xbfb8aa3b, v38
	v_mul_f32_e32 v135, 0xbfb8aa3b, v39
	v_mul_f32_e32 v136, 0xbfb8aa3b, v32
	v_mul_f32_e32 v137, 0xbfb8aa3b, v33
	v_exp_f32_e32 v134, v134
	v_exp_f32_e32 v135, v135
	v_exp_f32_e32 v136, v136
	v_exp_f32_e32 v137, v137
	v_exp_f32_e32 v138, v138
	v_exp_f32_e32 v139, v139
	v_pk_add_f32 v[134:135], v[134:135], 1.0 op_sel_hi:[1,0]
	s_nop 0
	v_pk_add_f32 v[136:137], v[136:137], 1.0 op_sel_hi:[1,0]
	s_nop 0
	v_rcp_f32_e32 v132, v132
	v_rcp_f32_e32 v133, v133
	v_rcp_f32_e32 v134, v134
	v_rcp_f32_e32 v135, v135
	v_rcp_f32_e32 v136, v136
	v_rcp_f32_e32 v137, v137
	v_pk_add_f32 v[138:139], v[138:139], 1.0 op_sel_hi:[1,0]
	s_nop 0
	v_rcp_f32_e32 v138, v138
	v_rcp_f32_e32 v139, v139
	v_cvt_pk_bf16_f32 v132, v132, v133
	v_cvt_pk_bf16_f32 v133, v134, v135
	v_cvt_pk_bf16_f32 v134, v136, v137
	v_mul_f32_e32 v136, 0xbfb8aa3b, v28
	v_mul_f32_e32 v137, 0xbfb8aa3b, v29
	v_exp_f32_e32 v136, v136
	v_exp_f32_e32 v137, v137
	v_cvt_pk_bf16_f32 v135, v138, v139
	global_store_dwordx4 v[130:131], v[132:135], off offset:3072
	v_add_f32_e32 v130, 1.0, v136
	v_add_f32_e32 v131, 1.0, v137
	v_mul_f32_e32 v132, 0xbfb8aa3b, v30
	v_mul_f32_e32 v133, 0xbfb8aa3b, v31
	v_mul_f32_e32 v134, 0xbfb8aa3b, v24
	v_mul_f32_e32 v135, 0xbfb8aa3b, v25
	v_exp_f32_e32 v132, v132
	v_exp_f32_e32 v133, v133
	v_exp_f32_e32 v134, v134
	v_exp_f32_e32 v135, v135
	v_mul_f32_e32 v136, 0xbfb8aa3b, v26
	v_mul_f32_e32 v137, 0xbfb8aa3b, v27
	v_exp_f32_e32 v136, v136
	v_exp_f32_e32 v137, v137
	v_pk_add_f32 v[132:133], v[132:133], 1.0 op_sel_hi:[1,0]
	s_nop 0
	v_pk_add_f32 v[134:135], v[134:135], 1.0 op_sel_hi:[1,0]
	s_nop 0
	v_rcp_f32_e32 v130, v130
	v_rcp_f32_e32 v131, v131
	v_rcp_f32_e32 v132, v132
	v_rcp_f32_e32 v133, v133
	v_rcp_f32_e32 v134, v134
	v_rcp_f32_e32 v135, v135
	v_pk_add_f32 v[136:137], v[136:137], 1.0 op_sel_hi:[1,0]
	s_nop 0
	v_rcp_f32_e32 v136, v136
	v_rcp_f32_e32 v137, v137
	v_cvt_pk_bf16_f32 v130, v130, v131
	v_cvt_pk_bf16_f32 v131, v132, v133
	v_cvt_pk_bf16_f32 v132, v134, v135
	v_add_co_u32_e32 v134, vcc, s34, v128
	v_cvt_pk_bf16_f32 v133, v136, v137
	s_nop 0
	v_addc_co_u32_e32 v135, vcc, 0, v129, vcc
	v_mul_f32_e32 v128, 0xbfb8aa3b, v20
	v_mul_f32_e32 v129, 0xbfb8aa3b, v21
	global_store_dwordx4 v[134:135], v[130:133], off
	v_exp_f32_e32 v128, v128
	v_exp_f32_e32 v129, v129
	v_mul_f32_e32 v130, 0xbfb8aa3b, v22
	v_mul_f32_e32 v131, 0xbfb8aa3b, v23
	v_mul_f32_e32 v132, 0xbfb8aa3b, v16
	v_mul_f32_e32 v133, 0xbfb8aa3b, v17
	v_exp_f32_e32 v130, v130
	v_exp_f32_e32 v131, v131
	v_exp_f32_e32 v132, v132
	v_exp_f32_e32 v133, v133
	v_mul_f32_e32 v136, 0xbfb8aa3b, v18
	v_mul_f32_e32 v137, 0xbfb8aa3b, v19
	v_pk_add_f32 v[128:129], v[128:129], 1.0 op_sel_hi:[1,0]
	s_nop 0
	v_pk_add_f32 v[130:131], v[130:131], 1.0 op_sel_hi:[1,0]
	s_nop 0
	v_pk_add_f32 v[132:133], v[132:133], 1.0 op_sel_hi:[1,0]
	s_nop 0
	v_exp_f32_e32 v136, v136
	v_exp_f32_e32 v137, v137
	v_rcp_f32_e32 v128, v128
	v_rcp_f32_e32 v129, v129
	v_rcp_f32_e32 v130, v130
	v_rcp_f32_e32 v131, v131
	v_rcp_f32_e32 v132, v132
	v_rcp_f32_e32 v133, v133
	v_pk_add_f32 v[136:137], v[136:137], 1.0 op_sel_hi:[1,0]
	s_nop 0
	v_rcp_f32_e32 v136, v136
	v_rcp_f32_e32 v137, v137
	v_cvt_pk_bf16_f32 v128, v128, v129
	v_cvt_pk_bf16_f32 v129, v130, v131
	v_cvt_pk_bf16_f32 v130, v132, v133
	v_mul_f32_e32 v132, 0xbfb8aa3b, v12
	v_mul_f32_e32 v133, 0xbfb8aa3b, v13
	v_exp_f32_e32 v132, v132
	v_exp_f32_e32 v133, v133
	v_cvt_pk_bf16_f32 v131, v136, v137
	global_store_dwordx4 v[134:135], v[128:131], off offset:1024
	v_mul_f32_e32 v136, 0xbfb8aa3b, v10
	v_mul_f32_e32 v137, 0xbfb8aa3b, v11
	v_add_f32_e32 v128, 1.0, v132
	v_add_f32_e32 v129, 1.0, v133
	v_mul_f32_e32 v130, 0xbfb8aa3b, v14
	v_mul_f32_e32 v131, 0xbfb8aa3b, v15
	v_mul_f32_e32 v132, 0xbfb8aa3b, v8
	v_mul_f32_e32 v133, 0xbfb8aa3b, v9
	v_exp_f32_e32 v130, v130
	v_exp_f32_e32 v131, v131
	v_exp_f32_e32 v132, v132
	v_exp_f32_e32 v133, v133
	v_pk_add_f32 v[130:131], v[130:131], 1.0 op_sel_hi:[1,0]
	s_nop 0
	v_pk_add_f32 v[132:133], v[132:133], 1.0 op_sel_hi:[1,0]
	s_nop 0
	v_exp_f32_e32 v136, v136
	v_exp_f32_e32 v137, v137
	v_rcp_f32_e32 v128, v128
	v_rcp_f32_e32 v129, v129
	v_rcp_f32_e32 v130, v130
	v_rcp_f32_e32 v131, v131
	v_rcp_f32_e32 v132, v132
	v_rcp_f32_e32 v133, v133
	v_pk_add_f32 v[136:137], v[136:137], 1.0 op_sel_hi:[1,0]
	s_nop 0
	v_rcp_f32_e32 v136, v136
	v_rcp_f32_e32 v137, v137
	v_cvt_pk_bf16_f32 v128, v128, v129
	v_cvt_pk_bf16_f32 v129, v130, v131
	v_cvt_pk_bf16_f32 v130, v132, v133
	v_mul_f32_e32 v132, 0xbfb8aa3b, v4
	v_mul_f32_e32 v133, 0xbfb8aa3b, v5
	v_exp_f32_e32 v132, v132
	v_exp_f32_e32 v133, v133
	v_cvt_pk_bf16_f32 v131, v136, v137
	global_store_dwordx4 v[134:135], v[128:131], off offset:2048
	v_mul_f32_e32 v136, 0xbfb8aa3b, v2
	v_mul_f32_e32 v137, 0xbfb8aa3b, v3
	v_add_f32_e32 v128, 1.0, v132
	v_add_f32_e32 v129, 1.0, v133
	v_mul_f32_e32 v130, 0xbfb8aa3b, v6
	v_mul_f32_e32 v131, 0xbfb8aa3b, v7
	v_mul_f32_e32 v132, 0xbfb8aa3b, v0
	v_mul_f32_e32 v133, 0xbfb8aa3b, v1
	v_exp_f32_e32 v130, v130
	v_exp_f32_e32 v131, v131
	v_exp_f32_e32 v132, v132
	v_exp_f32_e32 v133, v133
	v_exp_f32_e32 v136, v136
	v_exp_f32_e32 v137, v137
	v_pk_add_f32 v[130:131], v[130:131], 1.0 op_sel_hi:[1,0]
	s_nop 0
	v_pk_add_f32 v[132:133], v[132:133], 1.0 op_sel_hi:[1,0]
	s_nop 0
	v_pk_add_f32 v[136:137], v[136:137], 1.0 op_sel_hi:[1,0]
	s_nop 0
	v_rcp_f32_e32 v128, v128
	v_rcp_f32_e32 v129, v129
	v_rcp_f32_e32 v130, v130
	v_rcp_f32_e32 v131, v131
	v_rcp_f32_e32 v132, v132
	v_rcp_f32_e32 v133, v133
	v_rcp_f32_e32 v136, v136
	v_rcp_f32_e32 v137, v137
	v_cvt_pk_bf16_f32 v128, v128, v129
	v_cvt_pk_bf16_f32 v129, v130, v131
	v_cvt_pk_bf16_f32 v130, v132, v133
	v_cvt_pk_bf16_f32 v131, v136, v137
	global_store_dwordx4 v[134:135], v[128:131], off offset:3072
	s_mov_b64 s[10:11], 0

.LBB0_416:
	s_andn2_b64 vcc, exec, s[10:11]
	s_cbranch_vccnz .LBB0_418
	s_lshl_b32 s5, s97, 6
	s_lshl_b32 s10, s68, 8
	s_add_i32 s5, s5, s10
	s_lshl_b32 s10, s82, 5
	s_ashr_i32 s11, s10, 31
	v_mul_f32_e32 v136, 0xbfb8aa3b, v125
	s_lshl_b64 s[10:11], s[10:11], 1
	v_exp_f32_e32 v136, v136
	v_add_u32_e32 v130, s5, v157
	s_add_u32 s10, s16, s10
	v_lshlrev_b32_e32 v128, 3, v159
	s_addc_u32 s11, s17, s11
	v_ashrrev_i32_e32 v129, 31, v128
	v_ashrrev_i32_e32 v131, 31, v130
	v_lshl_add_u64 v[128:129], v[128:129], 1, s[10:11]
	v_mul_lo_u32 v131, s40, v131
	v_mul_lo_u32 v134, s41, v130
	v_mad_u64_u32 v[132:133], s[10:11], s40, v130, 0
	v_mul_f32_e32 v135, 0xbfb8aa3b, v124
	v_add3_u32 v133, v133, v131, v134
	v_add_f32_e32 v134, 1.0, v136
	v_exp_f32_e32 v135, v135
	v_rcp_f32_e32 v134, v134
	v_lshl_add_u64 v[136:137], v[132:133], 1, v[128:129]
	v_mul_f32_e32 v133, 0xbfb8aa3b, v126
	v_add_f32_e32 v131, 1.0, v135
	v_mul_f32_e32 v132, v125, v134
	v_mul_f32_e32 v134, 0xbfb8aa3b, v127
	v_mul_f32_e32 v135, 0xbfb8aa3b, v120
	v_mul_f32_e32 v138, 0xbfb8aa3b, v121
	v_exp_f32_e32 v133, v133
	v_exp_f32_e32 v134, v134
	v_exp_f32_e32 v135, v135
	v_exp_f32_e32 v138, v138
	v_add_f32_e32 v133, 1.0, v133
	v_pk_add_f32 v[134:135], v[134:135], 1.0 op_sel_hi:[1,0]
	s_nop 0
	v_add_f32_e32 v138, 1.0, v138
	v_rcp_f32_e32 v133, v133
	v_rcp_f32_e32 v134, v134
	v_rcp_f32_e32 v135, v135
	v_rcp_f32_e32 v138, v138
	v_mul_f32_e32 v139, 0xbfb8aa3b, v122
	v_mul_f32_e32 v140, 0xbfb8aa3b, v123
	v_mul_f32_e32 v133, v126, v133
	v_mul_f32_e32 v134, v127, v134
	v_mul_f32_e32 v135, v120, v135
	v_exp_f32_e32 v139, v139
	v_exp_f32_e32 v140, v140
	v_mul_f32_e32 v138, v121, v138
	v_cndmask_b32_e64 v133, v133, v126, s[38:39]
	v_cndmask_b32_e64 v134, v134, v127, s[38:39]
	v_cndmask_b32_e64 v135, v135, v120, s[38:39]
	v_cndmask_b32_e64 v138, v138, v121, s[38:39]
	v_cvt_pk_bf16_f32 v133, v133, v134
	v_cvt_pk_bf16_f32 v134, v135, v138
	v_mul_f32_e32 v135, 0xbfb8aa3b, v117
	v_exp_f32_e32 v138, v135
	v_add_f32_e32 v139, 1.0, v139
	v_add_f32_e32 v140, 1.0, v140
	v_rcp_f32_e32 v131, v131
	v_rcp_f32_e32 v139, v139
	v_rcp_f32_e32 v140, v140
	v_add_f32_e32 v138, 1.0, v138
	v_rcp_f32_e32 v138, v138
	v_mul_f32_e32 v131, v124, v131
	v_mul_f32_e32 v139, v122, v139
	v_mul_f32_e32 v140, v123, v140
	v_cndmask_b32_e64 v131, v131, v124, s[38:39]
	v_cndmask_b32_e64 v132, v132, v125, s[38:39]
	v_cndmask_b32_e64 v139, v139, v122, s[38:39]
	v_cndmask_b32_e64 v140, v140, v123, s[38:39]
	v_cvt_pk_bf16_f32 v132, v131, v132
	v_cvt_pk_bf16_f32 v135, v139, v140
	v_mul_f32_e32 v131, 0xbfb8aa3b, v116
	global_store_dwordx4 v[136:137], v[132:135], off
	v_mul_f32_e32 v139, 0xbfb8aa3b, v114
	v_mul_f32_e32 v140, 0xbfb8aa3b, v115
	v_mul_f32_e32 v132, v117, v138
	v_mul_f32_e32 v133, 0xbfb8aa3b, v118
	v_mul_f32_e32 v134, 0xbfb8aa3b, v119
	v_mul_f32_e32 v135, 0xbfb8aa3b, v112
	v_mul_f32_e32 v138, 0xbfb8aa3b, v113
	v_exp_f32_e32 v131, v131
	v_exp_f32_e32 v133, v133
	v_exp_f32_e32 v134, v134
	v_exp_f32_e32 v135, v135
	v_exp_f32_e32 v138, v138
	v_exp_f32_e32 v139, v139
	v_exp_f32_e32 v140, v140
	v_add_f32_e32 v131, 1.0, v131
	v_add_f32_e32 v133, 1.0, v133
	v_pk_add_f32 v[134:135], v[134:135], 1.0 op_sel_hi:[1,0]
	s_nop 0
	v_pk_add_f32 v[138:139], v[138:139], 1.0 op_sel_hi:[1,0]
	s_nop 0
	v_add_f32_e32 v140, 1.0, v140
	v_rcp_f32_e32 v131, v131
	v_rcp_f32_e32 v133, v133
	v_rcp_f32_e32 v134, v134
	v_rcp_f32_e32 v135, v135
	v_rcp_f32_e32 v138, v138
	v_rcp_f32_e32 v139, v139
	v_rcp_f32_e32 v140, v140
	v_mul_f32_e32 v131, v116, v131
	v_mul_f32_e32 v133, v118, v133
	v_mul_f32_e32 v134, v119, v134
	v_mul_f32_e32 v135, v112, v135
	v_mul_f32_e32 v138, v113, v138
	v_mul_f32_e32 v139, v114, v139
	v_mul_f32_e32 v140, v115, v140
	v_cndmask_b32_e64 v131, v131, v116, s[38:39]
	v_cndmask_b32_e64 v132, v132, v117, s[38:39]
	v_cndmask_b32_e64 v133, v133, v118, s[38:39]
	v_cndmask_b32_e64 v134, v134, v119, s[38:39]
	v_cndmask_b32_e64 v135, v135, v112, s[38:39]
	v_cndmask_b32_e64 v138, v138, v113, s[38:39]
	v_cndmask_b32_e64 v139, v139, v114, s[38:39]
	v_cndmask_b32_e64 v140, v140, v115, s[38:39]
	v_cvt_pk_bf16_f32 v132, v131, v132
	v_cvt_pk_bf16_f32 v133, v133, v134
	v_cvt_pk_bf16_f32 v134, v135, v138
	v_cvt_pk_bf16_f32 v135, v139, v140
	global_store_dwordx4 v[136:137], v[132:135], off offset:256
	v_mul_f32_e32 v136, 0xbfb8aa3b, v109
	v_exp_f32_e32 v136, v136
	v_add_u32_e32 v131, 16, v130
	v_ashrrev_i32_e32 v132, 31, v131
	v_mul_lo_u32 v134, s40, v132
	v_mul_lo_u32 v135, s41, v131
	v_mad_u64_u32 v[132:133], s[10:11], s40, v131, 0
	v_add3_u32 v133, v133, v134, v135
	v_add_f32_e32 v134, 1.0, v136
	v_rcp_f32_e32 v134, v134
	v_lshl_add_u64 v[136:137], v[132:133], 1, v[128:129]
	v_mul_f32_e32 v133, 0xbfb8aa3b, v110
	v_mul_f32_e32 v135, 0xbfb8aa3b, v104
	v_mul_f32_e32 v132, v109, v134
	v_mul_f32_e32 v134, 0xbfb8aa3b, v111
	v_mul_f32_e32 v138, 0xbfb8aa3b, v105
	v_exp_f32_e32 v133, v133
	v_exp_f32_e32 v134, v134
	v_exp_f32_e32 v135, v135
	v_exp_f32_e32 v138, v138
	v_add_f32_e32 v133, 1.0, v133
	v_pk_add_f32 v[134:135], v[134:135], 1.0 op_sel_hi:[1,0]
	s_nop 0
	v_add_f32_e32 v138, 1.0, v138
	v_rcp_f32_e32 v133, v133
	v_rcp_f32_e32 v134, v134
	v_rcp_f32_e32 v135, v135
	v_rcp_f32_e32 v138, v138
	v_mul_f32_e32 v131, 0xbfb8aa3b, v108
	v_mul_f32_e32 v139, 0xbfb8aa3b, v106
	v_mul_f32_e32 v140, 0xbfb8aa3b, v107
	v_exp_f32_e32 v131, v131
	v_mul_f32_e32 v133, v110, v133
	v_mul_f32_e32 v134, v111, v134
	v_mul_f32_e32 v135, v104, v135
	v_exp_f32_e32 v139, v139
	v_exp_f32_e32 v140, v140
	v_mul_f32_e32 v138, v105, v138
	v_cndmask_b32_e64 v133, v133, v110, s[38:39]
	v_cndmask_b32_e64 v134, v134, v111, s[38:39]
	v_cndmask_b32_e64 v135, v135, v104, s[38:39]
	v_cndmask_b32_e64 v138, v138, v105, s[38:39]
	v_cvt_pk_bf16_f32 v133, v133, v134
	v_cvt_pk_bf16_f32 v134, v135, v138
	v_mul_f32_e32 v135, 0xbfb8aa3b, v101
	v_exp_f32_e32 v138, v135
	v_add_f32_e32 v131, 1.0, v131
	v_add_f32_e32 v139, 1.0, v139
	v_add_f32_e32 v140, 1.0, v140
	v_rcp_f32_e32 v131, v131
	v_rcp_f32_e32 v139, v139
	v_rcp_f32_e32 v140, v140
	v_add_f32_e32 v138, 1.0, v138
	v_rcp_f32_e32 v138, v138
	v_mul_f32_e32 v131, v108, v131
	v_mul_f32_e32 v139, v106, v139
	v_mul_f32_e32 v140, v107, v140
	v_cndmask_b32_e64 v131, v131, v108, s[38:39]
	v_cndmask_b32_e64 v132, v132, v109, s[38:39]
	v_cndmask_b32_e64 v139, v139, v106, s[38:39]
	v_cndmask_b32_e64 v140, v140, v107, s[38:39]
	v_cvt_pk_bf16_f32 v132, v131, v132
	v_cvt_pk_bf16_f32 v135, v139, v140
	v_mul_f32_e32 v131, 0xbfb8aa3b, v100
	global_store_dwordx4 v[136:137], v[132:135], off
	v_mul_f32_e32 v139, 0xbfb8aa3b, v98
	v_mul_f32_e32 v140, 0xbfb8aa3b, v99
	v_mul_f32_e32 v132, v101, v138
	v_mul_f32_e32 v133, 0xbfb8aa3b, v102
	v_mul_f32_e32 v134, 0xbfb8aa3b, v103
	v_mul_f32_e32 v135, 0xbfb8aa3b, v96
	v_mul_f32_e32 v138, 0xbfb8aa3b, v97
	v_exp_f32_e32 v131, v131
	v_exp_f32_e32 v133, v133
	v_exp_f32_e32 v134, v134
	v_exp_f32_e32 v135, v135
	v_exp_f32_e32 v138, v138
	v_exp_f32_e32 v139, v139
	v_exp_f32_e32 v140, v140
	v_add_f32_e32 v131, 1.0, v131
	v_add_f32_e32 v133, 1.0, v133
	v_pk_add_f32 v[134:135], v[134:135], 1.0 op_sel_hi:[1,0]
	s_nop 0
	v_pk_add_f32 v[138:139], v[138:139], 1.0 op_sel_hi:[1,0]
	s_nop 0
	v_add_f32_e32 v140, 1.0, v140
	v_rcp_f32_e32 v131, v131
	v_rcp_f32_e32 v133, v133
	v_rcp_f32_e32 v134, v134
	v_rcp_f32_e32 v135, v135
	v_rcp_f32_e32 v138, v138
	v_rcp_f32_e32 v139, v139
	v_rcp_f32_e32 v140, v140
	v_mul_f32_e32 v131, v100, v131
	v_mul_f32_e32 v133, v102, v133
	v_mul_f32_e32 v134, v103, v134
	v_mul_f32_e32 v135, v96, v135
	v_mul_f32_e32 v138, v97, v138
	v_mul_f32_e32 v139, v98, v139
	v_mul_f32_e32 v140, v99, v140
	v_cndmask_b32_e64 v131, v131, v100, s[38:39]
	v_cndmask_b32_e64 v132, v132, v101, s[38:39]
	v_cndmask_b32_e64 v133, v133, v102, s[38:39]
	v_cndmask_b32_e64 v134, v134, v103, s[38:39]
	v_cndmask_b32_e64 v135, v135, v96, s[38:39]
	v_cndmask_b32_e64 v138, v138, v97, s[38:39]
	v_cndmask_b32_e64 v139, v139, v98, s[38:39]
	v_cndmask_b32_e64 v140, v140, v99, s[38:39]
	v_cvt_pk_bf16_f32 v132, v131, v132
	v_cvt_pk_bf16_f32 v133, v133, v134
	v_cvt_pk_bf16_f32 v134, v135, v138
	v_cvt_pk_bf16_f32 v135, v139, v140
	global_store_dwordx4 v[136:137], v[132:135], off offset:256
	v_mul_f32_e32 v136, 0xbfb8aa3b, v93
	v_exp_f32_e32 v136, v136
	v_add_u32_e32 v131, 32, v130
	v_ashrrev_i32_e32 v132, 31, v131
	v_mul_lo_u32 v134, s40, v132
	v_mul_lo_u32 v135, s41, v131
	v_mad_u64_u32 v[132:133], s[10:11], s40, v131, 0
	v_add3_u32 v133, v133, v134, v135
	v_add_f32_e32 v134, 1.0, v136
	v_rcp_f32_e32 v134, v134
	v_lshl_add_u64 v[136:137], v[132:133], 1, v[128:129]
	v_mul_f32_e32 v133, 0xbfb8aa3b, v94
	v_mul_f32_e32 v135, 0xbfb8aa3b, v88
	v_mul_f32_e32 v132, v93, v134
	v_mul_f32_e32 v134, 0xbfb8aa3b, v95
	v_mul_f32_e32 v138, 0xbfb8aa3b, v89
	v_exp_f32_e32 v133, v133
	v_exp_f32_e32 v134, v134
	v_exp_f32_e32 v135, v135
	v_exp_f32_e32 v138, v138
	v_add_f32_e32 v133, 1.0, v133
	v_pk_add_f32 v[134:135], v[134:135], 1.0 op_sel_hi:[1,0]
	s_nop 0
	v_add_f32_e32 v138, 1.0, v138
	v_rcp_f32_e32 v133, v133
	v_rcp_f32_e32 v134, v134
	v_rcp_f32_e32 v135, v135
	v_rcp_f32_e32 v138, v138
	v_mul_f32_e32 v131, 0xbfb8aa3b, v92
	v_mul_f32_e32 v139, 0xbfb8aa3b, v90
	v_mul_f32_e32 v140, 0xbfb8aa3b, v91
	v_exp_f32_e32 v131, v131
	v_mul_f32_e32 v133, v94, v133
	v_mul_f32_e32 v134, v95, v134
	v_mul_f32_e32 v135, v88, v135
	v_exp_f32_e32 v139, v139
	v_exp_f32_e32 v140, v140
	v_mul_f32_e32 v138, v89, v138
	v_cndmask_b32_e64 v133, v133, v94, s[38:39]
	v_cndmask_b32_e64 v134, v134, v95, s[38:39]
	v_cndmask_b32_e64 v135, v135, v88, s[38:39]
	v_cndmask_b32_e64 v138, v138, v89, s[38:39]
	v_cvt_pk_bf16_f32 v133, v133, v134
	v_cvt_pk_bf16_f32 v134, v135, v138
	v_mul_f32_e32 v135, 0xbfb8aa3b, v85
	v_exp_f32_e32 v138, v135
	v_add_f32_e32 v131, 1.0, v131
	v_add_f32_e32 v139, 1.0, v139
	v_add_f32_e32 v140, 1.0, v140
	v_rcp_f32_e32 v131, v131
	v_rcp_f32_e32 v139, v139
	v_rcp_f32_e32 v140, v140
	v_add_f32_e32 v138, 1.0, v138
	v_rcp_f32_e32 v138, v138
	v_mul_f32_e32 v131, v92, v131
	v_mul_f32_e32 v139, v90, v139
	v_mul_f32_e32 v140, v91, v140
	v_cndmask_b32_e64 v131, v131, v92, s[38:39]
	v_cndmask_b32_e64 v132, v132, v93, s[38:39]
	v_cndmask_b32_e64 v139, v139, v90, s[38:39]
	v_cndmask_b32_e64 v140, v140, v91, s[38:39]
	v_cvt_pk_bf16_f32 v132, v131, v132
	v_cvt_pk_bf16_f32 v135, v139, v140
	v_mul_f32_e32 v131, 0xbfb8aa3b, v84
	global_store_dwordx4 v[136:137], v[132:135], off
	v_mul_f32_e32 v139, 0xbfb8aa3b, v82
	v_mul_f32_e32 v140, 0xbfb8aa3b, v83
	v_mul_f32_e32 v132, v85, v138
	v_mul_f32_e32 v133, 0xbfb8aa3b, v86
	v_mul_f32_e32 v134, 0xbfb8aa3b, v87
	v_mul_f32_e32 v135, 0xbfb8aa3b, v80
	v_mul_f32_e32 v138, 0xbfb8aa3b, v81
	v_exp_f32_e32 v131, v131
	v_exp_f32_e32 v133, v133
	v_exp_f32_e32 v134, v134
	v_exp_f32_e32 v135, v135
	v_exp_f32_e32 v138, v138
	v_exp_f32_e32 v139, v139
	v_exp_f32_e32 v140, v140
	v_add_f32_e32 v131, 1.0, v131
	v_add_f32_e32 v133, 1.0, v133
	v_pk_add_f32 v[134:135], v[134:135], 1.0 op_sel_hi:[1,0]
	s_nop 0
	v_pk_add_f32 v[138:139], v[138:139], 1.0 op_sel_hi:[1,0]
	s_nop 0
	v_add_f32_e32 v140, 1.0, v140
	v_rcp_f32_e32 v131, v131
	v_rcp_f32_e32 v133, v133
	v_rcp_f32_e32 v134, v134
	v_rcp_f32_e32 v135, v135
	v_rcp_f32_e32 v138, v138
	v_rcp_f32_e32 v139, v139
	v_rcp_f32_e32 v140, v140
	v_mul_f32_e32 v131, v84, v131
	v_mul_f32_e32 v133, v86, v133
	v_mul_f32_e32 v134, v87, v134
	v_mul_f32_e32 v135, v80, v135
	v_mul_f32_e32 v138, v81, v138
	v_mul_f32_e32 v139, v82, v139
	v_mul_f32_e32 v140, v83, v140
	v_cndmask_b32_e64 v131, v131, v84, s[38:39]
	v_cndmask_b32_e64 v132, v132, v85, s[38:39]
	v_cndmask_b32_e64 v133, v133, v86, s[38:39]
	v_cndmask_b32_e64 v134, v134, v87, s[38:39]
	v_cndmask_b32_e64 v135, v135, v80, s[38:39]
	v_cndmask_b32_e64 v138, v138, v81, s[38:39]
	v_cndmask_b32_e64 v139, v139, v82, s[38:39]
	v_cndmask_b32_e64 v140, v140, v83, s[38:39]
	v_cvt_pk_bf16_f32 v132, v131, v132
	v_cvt_pk_bf16_f32 v133, v133, v134
	v_cvt_pk_bf16_f32 v134, v135, v138
	v_cvt_pk_bf16_f32 v135, v139, v140
	global_store_dwordx4 v[136:137], v[132:135], off offset:256
	v_mul_f32_e32 v136, 0xbfb8aa3b, v77
	v_exp_f32_e32 v136, v136
	v_add_u32_e32 v131, 48, v130
	v_ashrrev_i32_e32 v132, 31, v131
	v_mul_lo_u32 v134, s40, v132
	v_mul_lo_u32 v135, s41, v131
	v_mad_u64_u32 v[132:133], s[10:11], s40, v131, 0
	v_add3_u32 v133, v133, v134, v135
	v_add_f32_e32 v134, 1.0, v136
	v_rcp_f32_e32 v134, v134
	v_lshl_add_u64 v[136:137], v[132:133], 1, v[128:129]
	v_mul_f32_e32 v133, 0xbfb8aa3b, v78
	v_mul_f32_e32 v135, 0xbfb8aa3b, v72
	v_mul_f32_e32 v132, v77, v134
	v_mul_f32_e32 v134, 0xbfb8aa3b, v79
	v_mul_f32_e32 v138, 0xbfb8aa3b, v73
	v_exp_f32_e32 v133, v133
	v_exp_f32_e32 v134, v134
	v_exp_f32_e32 v135, v135
	v_exp_f32_e32 v138, v138
	v_add_f32_e32 v133, 1.0, v133
	v_pk_add_f32 v[134:135], v[134:135], 1.0 op_sel_hi:[1,0]
	s_nop 0
	v_add_f32_e32 v138, 1.0, v138
	v_rcp_f32_e32 v133, v133
	v_rcp_f32_e32 v134, v134
	v_rcp_f32_e32 v135, v135
	v_rcp_f32_e32 v138, v138
	v_mul_f32_e32 v131, 0xbfb8aa3b, v76
	v_mul_f32_e32 v139, 0xbfb8aa3b, v74
	v_mul_f32_e32 v140, 0xbfb8aa3b, v75
	v_exp_f32_e32 v131, v131
	v_mul_f32_e32 v133, v78, v133
	v_mul_f32_e32 v134, v79, v134
	v_mul_f32_e32 v135, v72, v135
	v_exp_f32_e32 v139, v139
	v_exp_f32_e32 v140, v140
	v_mul_f32_e32 v138, v73, v138
	v_cndmask_b32_e64 v133, v133, v78, s[38:39]
	v_cndmask_b32_e64 v134, v134, v79, s[38:39]
	v_cndmask_b32_e64 v135, v135, v72, s[38:39]
	v_cndmask_b32_e64 v138, v138, v73, s[38:39]
	v_cvt_pk_bf16_f32 v133, v133, v134
	v_cvt_pk_bf16_f32 v134, v135, v138
	v_mul_f32_e32 v135, 0xbfb8aa3b, v69
	v_exp_f32_e32 v138, v135
	v_add_f32_e32 v131, 1.0, v131
	v_add_f32_e32 v139, 1.0, v139
	v_add_f32_e32 v140, 1.0, v140
	v_rcp_f32_e32 v131, v131
	v_rcp_f32_e32 v139, v139
	v_rcp_f32_e32 v140, v140
	v_add_f32_e32 v138, 1.0, v138
	v_rcp_f32_e32 v138, v138
	v_mul_f32_e32 v131, v76, v131
	v_mul_f32_e32 v139, v74, v139
	v_mul_f32_e32 v140, v75, v140
	v_cndmask_b32_e64 v131, v131, v76, s[38:39]
	v_cndmask_b32_e64 v132, v132, v77, s[38:39]
	v_cndmask_b32_e64 v139, v139, v74, s[38:39]
	v_cndmask_b32_e64 v140, v140, v75, s[38:39]
	v_cvt_pk_bf16_f32 v132, v131, v132
	v_cvt_pk_bf16_f32 v135, v139, v140
	v_mul_f32_e32 v131, 0xbfb8aa3b, v68
	global_store_dwordx4 v[136:137], v[132:135], off
	v_mul_f32_e32 v139, 0xbfb8aa3b, v66
	v_mul_f32_e32 v140, 0xbfb8aa3b, v67
	v_mul_f32_e32 v132, v69, v138
	v_mul_f32_e32 v133, 0xbfb8aa3b, v70
	v_mul_f32_e32 v134, 0xbfb8aa3b, v71
	v_mul_f32_e32 v135, 0xbfb8aa3b, v64
	v_mul_f32_e32 v138, 0xbfb8aa3b, v65
	v_exp_f32_e32 v131, v131
	v_exp_f32_e32 v133, v133
	v_exp_f32_e32 v134, v134
	v_exp_f32_e32 v135, v135
	v_exp_f32_e32 v138, v138
	v_exp_f32_e32 v139, v139
	v_exp_f32_e32 v140, v140
	v_add_f32_e32 v131, 1.0, v131
	v_add_f32_e32 v133, 1.0, v133
	v_pk_add_f32 v[134:135], v[134:135], 1.0 op_sel_hi:[1,0]
	s_nop 0
	v_pk_add_f32 v[138:139], v[138:139], 1.0 op_sel_hi:[1,0]
	s_nop 0
	v_add_f32_e32 v140, 1.0, v140
	v_rcp_f32_e32 v131, v131
	v_rcp_f32_e32 v133, v133
	v_rcp_f32_e32 v134, v134
	v_rcp_f32_e32 v135, v135
	v_rcp_f32_e32 v138, v138
	v_rcp_f32_e32 v139, v139
	v_rcp_f32_e32 v140, v140
	v_mul_f32_e32 v131, v68, v131
	v_mul_f32_e32 v133, v70, v133
	v_mul_f32_e32 v134, v71, v134
	v_mul_f32_e32 v135, v64, v135
	v_mul_f32_e32 v138, v65, v138
	v_mul_f32_e32 v139, v66, v139
	v_mul_f32_e32 v140, v67, v140
	v_cndmask_b32_e64 v131, v131, v68, s[38:39]
	v_cndmask_b32_e64 v132, v132, v69, s[38:39]
	v_cndmask_b32_e64 v133, v133, v70, s[38:39]
	v_cndmask_b32_e64 v134, v134, v71, s[38:39]
	v_cndmask_b32_e64 v135, v135, v64, s[38:39]
	v_cndmask_b32_e64 v138, v138, v65, s[38:39]
	v_cndmask_b32_e64 v139, v139, v66, s[38:39]
	v_cndmask_b32_e64 v140, v140, v67, s[38:39]
	v_cvt_pk_bf16_f32 v132, v131, v132
	v_cvt_pk_bf16_f32 v133, v133, v134
	v_cvt_pk_bf16_f32 v134, v135, v138
	v_cvt_pk_bf16_f32 v135, v139, v140
	global_store_dwordx4 v[136:137], v[132:135], off offset:256
	v_mul_f32_e32 v136, 0xbfb8aa3b, v61
	v_exp_f32_e32 v136, v136
	v_add_u32_e32 v131, 0x80, v130
	v_ashrrev_i32_e32 v132, 31, v131
	v_mul_lo_u32 v134, s40, v132
	v_mul_lo_u32 v135, s41, v131
	v_mad_u64_u32 v[132:133], s[10:11], s40, v131, 0
	v_add3_u32 v133, v133, v134, v135
	v_add_f32_e32 v134, 1.0, v136
	v_rcp_f32_e32 v134, v134
	v_lshl_add_u64 v[136:137], v[132:133], 1, v[128:129]
	v_mul_f32_e32 v133, 0xbfb8aa3b, v62
	v_mul_f32_e32 v135, 0xbfb8aa3b, v56
	v_mul_f32_e32 v132, v61, v134
	v_mul_f32_e32 v134, 0xbfb8aa3b, v63
	v_mul_f32_e32 v138, 0xbfb8aa3b, v57
	v_exp_f32_e32 v133, v133
	v_exp_f32_e32 v134, v134
	v_exp_f32_e32 v135, v135
	v_exp_f32_e32 v138, v138
	v_add_f32_e32 v133, 1.0, v133
	v_pk_add_f32 v[134:135], v[134:135], 1.0 op_sel_hi:[1,0]
	s_nop 0
	v_add_f32_e32 v138, 1.0, v138
	v_rcp_f32_e32 v133, v133
	v_rcp_f32_e32 v134, v134
	v_rcp_f32_e32 v135, v135
	v_rcp_f32_e32 v138, v138
	v_mul_f32_e32 v131, 0xbfb8aa3b, v60
	v_mul_f32_e32 v139, 0xbfb8aa3b, v58
	v_mul_f32_e32 v140, 0xbfb8aa3b, v59
	v_exp_f32_e32 v131, v131
	v_mul_f32_e32 v133, v62, v133
	v_mul_f32_e32 v134, v63, v134
	v_mul_f32_e32 v135, v56, v135
	v_exp_f32_e32 v139, v139
	v_exp_f32_e32 v140, v140
	v_mul_f32_e32 v138, v57, v138
	v_cndmask_b32_e64 v133, v133, v62, s[38:39]
	v_cndmask_b32_e64 v134, v134, v63, s[38:39]
	v_cndmask_b32_e64 v135, v135, v56, s[38:39]
	v_cndmask_b32_e64 v138, v138, v57, s[38:39]
	v_cvt_pk_bf16_f32 v133, v133, v134
	v_cvt_pk_bf16_f32 v134, v135, v138
	v_mul_f32_e32 v135, 0xbfb8aa3b, v53
	v_exp_f32_e32 v138, v135
	v_add_f32_e32 v131, 1.0, v131
	v_add_f32_e32 v139, 1.0, v139
	v_add_f32_e32 v140, 1.0, v140
	v_rcp_f32_e32 v131, v131
	v_rcp_f32_e32 v139, v139
	v_rcp_f32_e32 v140, v140
	v_add_f32_e32 v138, 1.0, v138
	v_rcp_f32_e32 v138, v138
	v_mul_f32_e32 v131, v60, v131
	v_mul_f32_e32 v139, v58, v139
	v_mul_f32_e32 v140, v59, v140
	v_cndmask_b32_e64 v131, v131, v60, s[38:39]
	v_cndmask_b32_e64 v132, v132, v61, s[38:39]
	v_cndmask_b32_e64 v139, v139, v58, s[38:39]
	v_cndmask_b32_e64 v140, v140, v59, s[38:39]
	v_cvt_pk_bf16_f32 v132, v131, v132
	v_cvt_pk_bf16_f32 v135, v139, v140
	v_mul_f32_e32 v131, 0xbfb8aa3b, v52
	global_store_dwordx4 v[136:137], v[132:135], off
	v_mul_f32_e32 v139, 0xbfb8aa3b, v50
	v_mul_f32_e32 v140, 0xbfb8aa3b, v51
	v_mul_f32_e32 v132, v53, v138
	v_mul_f32_e32 v133, 0xbfb8aa3b, v54
	v_mul_f32_e32 v134, 0xbfb8aa3b, v55
	v_mul_f32_e32 v135, 0xbfb8aa3b, v48
	v_mul_f32_e32 v138, 0xbfb8aa3b, v49
	v_exp_f32_e32 v131, v131
	v_exp_f32_e32 v133, v133
	v_exp_f32_e32 v134, v134
	v_exp_f32_e32 v135, v135
	v_exp_f32_e32 v138, v138
	v_exp_f32_e32 v139, v139
	v_exp_f32_e32 v140, v140
	v_add_f32_e32 v131, 1.0, v131
	v_add_f32_e32 v133, 1.0, v133
	v_pk_add_f32 v[134:135], v[134:135], 1.0 op_sel_hi:[1,0]
	s_nop 0
	v_pk_add_f32 v[138:139], v[138:139], 1.0 op_sel_hi:[1,0]
	s_nop 0
	v_add_f32_e32 v140, 1.0, v140
	v_rcp_f32_e32 v131, v131
	v_rcp_f32_e32 v133, v133
	v_rcp_f32_e32 v134, v134
	v_rcp_f32_e32 v135, v135
	v_rcp_f32_e32 v138, v138
	v_rcp_f32_e32 v139, v139
	v_rcp_f32_e32 v140, v140
	v_mul_f32_e32 v131, v52, v131
	v_mul_f32_e32 v133, v54, v133
	v_mul_f32_e32 v134, v55, v134
	v_mul_f32_e32 v135, v48, v135
	v_mul_f32_e32 v138, v49, v138
	v_mul_f32_e32 v139, v50, v139
	v_mul_f32_e32 v140, v51, v140
	v_cndmask_b32_e64 v131, v131, v52, s[38:39]
	v_cndmask_b32_e64 v132, v132, v53, s[38:39]
	v_cndmask_b32_e64 v133, v133, v54, s[38:39]
	v_cndmask_b32_e64 v134, v134, v55, s[38:39]
	v_cndmask_b32_e64 v135, v135, v48, s[38:39]
	v_cndmask_b32_e64 v138, v138, v49, s[38:39]
	v_cndmask_b32_e64 v139, v139, v50, s[38:39]
	v_cndmask_b32_e64 v140, v140, v51, s[38:39]
	v_cvt_pk_bf16_f32 v132, v131, v132
	v_cvt_pk_bf16_f32 v133, v133, v134
	v_cvt_pk_bf16_f32 v134, v135, v138
	v_cvt_pk_bf16_f32 v135, v139, v140
	global_store_dwordx4 v[136:137], v[132:135], off offset:256
	v_mul_f32_e32 v136, 0xbfb8aa3b, v45
	v_exp_f32_e32 v136, v136
	v_add_u32_e32 v131, 0x90, v130
	v_ashrrev_i32_e32 v132, 31, v131
	v_mul_lo_u32 v134, s40, v132
	v_mul_lo_u32 v135, s41, v131
	v_mad_u64_u32 v[132:133], s[10:11], s40, v131, 0
	v_add3_u32 v133, v133, v134, v135
	v_add_f32_e32 v134, 1.0, v136
	v_rcp_f32_e32 v134, v134
	v_lshl_add_u64 v[136:137], v[132:133], 1, v[128:129]
	v_mul_f32_e32 v133, 0xbfb8aa3b, v46
	v_mul_f32_e32 v135, 0xbfb8aa3b, v40
	v_mul_f32_e32 v132, v45, v134
	v_mul_f32_e32 v134, 0xbfb8aa3b, v47
	v_mul_f32_e32 v138, 0xbfb8aa3b, v41
	v_exp_f32_e32 v133, v133
	v_exp_f32_e32 v134, v134
	v_exp_f32_e32 v135, v135
	v_exp_f32_e32 v138, v138
	v_add_f32_e32 v133, 1.0, v133
	v_pk_add_f32 v[134:135], v[134:135], 1.0 op_sel_hi:[1,0]
	s_nop 0
	v_add_f32_e32 v138, 1.0, v138
	v_rcp_f32_e32 v133, v133
	v_rcp_f32_e32 v134, v134
	v_rcp_f32_e32 v135, v135
	v_rcp_f32_e32 v138, v138
	v_mul_f32_e32 v131, 0xbfb8aa3b, v44
	v_mul_f32_e32 v139, 0xbfb8aa3b, v42
	v_mul_f32_e32 v140, 0xbfb8aa3b, v43
	v_exp_f32_e32 v131, v131
	v_mul_f32_e32 v133, v46, v133
	v_mul_f32_e32 v134, v47, v134
	v_mul_f32_e32 v135, v40, v135
	v_exp_f32_e32 v139, v139
	v_exp_f32_e32 v140, v140
	v_mul_f32_e32 v138, v41, v138
	v_cndmask_b32_e64 v133, v133, v46, s[38:39]
	v_cndmask_b32_e64 v134, v134, v47, s[38:39]
	v_cndmask_b32_e64 v135, v135, v40, s[38:39]
	v_cndmask_b32_e64 v138, v138, v41, s[38:39]
	v_cvt_pk_bf16_f32 v133, v133, v134
	v_cvt_pk_bf16_f32 v134, v135, v138
	v_mul_f32_e32 v135, 0xbfb8aa3b, v37
	v_exp_f32_e32 v138, v135
	v_add_f32_e32 v131, 1.0, v131
	v_add_f32_e32 v139, 1.0, v139
	v_add_f32_e32 v140, 1.0, v140
	v_rcp_f32_e32 v131, v131
	v_rcp_f32_e32 v139, v139
	v_rcp_f32_e32 v140, v140
	v_add_f32_e32 v138, 1.0, v138
	v_rcp_f32_e32 v138, v138
	v_mul_f32_e32 v131, v44, v131
	v_mul_f32_e32 v139, v42, v139
	v_mul_f32_e32 v140, v43, v140
	v_cndmask_b32_e64 v131, v131, v44, s[38:39]
	v_cndmask_b32_e64 v132, v132, v45, s[38:39]
	v_cndmask_b32_e64 v139, v139, v42, s[38:39]
	v_cndmask_b32_e64 v140, v140, v43, s[38:39]
	v_cvt_pk_bf16_f32 v132, v131, v132
	v_cvt_pk_bf16_f32 v135, v139, v140
	v_mul_f32_e32 v131, 0xbfb8aa3b, v36
	global_store_dwordx4 v[136:137], v[132:135], off
	v_mul_f32_e32 v139, 0xbfb8aa3b, v34
	v_mul_f32_e32 v140, 0xbfb8aa3b, v35
	v_mul_f32_e32 v132, v37, v138
	v_mul_f32_e32 v133, 0xbfb8aa3b, v38
	v_mul_f32_e32 v134, 0xbfb8aa3b, v39
	v_mul_f32_e32 v135, 0xbfb8aa3b, v32
	v_mul_f32_e32 v138, 0xbfb8aa3b, v33
	v_exp_f32_e32 v131, v131
	v_exp_f32_e32 v133, v133
	v_exp_f32_e32 v134, v134
	v_exp_f32_e32 v135, v135
	v_exp_f32_e32 v138, v138
	v_exp_f32_e32 v139, v139
	v_exp_f32_e32 v140, v140
	v_add_f32_e32 v131, 1.0, v131
	v_add_f32_e32 v133, 1.0, v133
	v_pk_add_f32 v[134:135], v[134:135], 1.0 op_sel_hi:[1,0]
	s_nop 0
	v_pk_add_f32 v[138:139], v[138:139], 1.0 op_sel_hi:[1,0]
	s_nop 0
	v_add_f32_e32 v140, 1.0, v140
	v_rcp_f32_e32 v131, v131
	v_rcp_f32_e32 v133, v133
	v_rcp_f32_e32 v134, v134
	v_rcp_f32_e32 v135, v135
	v_rcp_f32_e32 v138, v138
	v_rcp_f32_e32 v139, v139
	v_rcp_f32_e32 v140, v140
	v_mul_f32_e32 v131, v36, v131
	v_mul_f32_e32 v133, v38, v133
	v_mul_f32_e32 v134, v39, v134
	v_mul_f32_e32 v135, v32, v135
	v_mul_f32_e32 v138, v33, v138
	v_mul_f32_e32 v139, v34, v139
	v_mul_f32_e32 v140, v35, v140
	v_cndmask_b32_e64 v131, v131, v36, s[38:39]
	v_cndmask_b32_e64 v132, v132, v37, s[38:39]
	v_cndmask_b32_e64 v133, v133, v38, s[38:39]
	v_cndmask_b32_e64 v134, v134, v39, s[38:39]
	v_cndmask_b32_e64 v135, v135, v32, s[38:39]
	v_cndmask_b32_e64 v138, v138, v33, s[38:39]
	v_cndmask_b32_e64 v139, v139, v34, s[38:39]
	v_cndmask_b32_e64 v140, v140, v35, s[38:39]
	v_cvt_pk_bf16_f32 v132, v131, v132
	v_cvt_pk_bf16_f32 v133, v133, v134
	v_cvt_pk_bf16_f32 v134, v135, v138
	v_cvt_pk_bf16_f32 v135, v139, v140
	global_store_dwordx4 v[136:137], v[132:135], off offset:256
	v_mul_f32_e32 v136, 0xbfb8aa3b, v29
	v_exp_f32_e32 v136, v136
	v_add_u32_e32 v131, 0xa0, v130
	v_ashrrev_i32_e32 v132, 31, v131
	v_mul_lo_u32 v134, s40, v132
	v_mul_lo_u32 v135, s41, v131
	v_mad_u64_u32 v[132:133], s[10:11], s40, v131, 0
	v_add3_u32 v133, v133, v134, v135
	v_add_f32_e32 v134, 1.0, v136
	v_rcp_f32_e32 v134, v134
	v_lshl_add_u64 v[136:137], v[132:133], 1, v[128:129]
	v_mul_f32_e32 v133, 0xbfb8aa3b, v30
	v_mul_f32_e32 v135, 0xbfb8aa3b, v24
	v_mul_f32_e32 v132, v29, v134
	v_mul_f32_e32 v134, 0xbfb8aa3b, v31
	v_mul_f32_e32 v138, 0xbfb8aa3b, v25
	v_exp_f32_e32 v133, v133
	v_exp_f32_e32 v134, v134
	v_exp_f32_e32 v135, v135
	v_exp_f32_e32 v138, v138
	v_add_f32_e32 v133, 1.0, v133
	v_pk_add_f32 v[134:135], v[134:135], 1.0 op_sel_hi:[1,0]
	s_nop 0
	v_add_f32_e32 v138, 1.0, v138
	v_rcp_f32_e32 v133, v133
	v_rcp_f32_e32 v134, v134
	v_rcp_f32_e32 v135, v135
	v_rcp_f32_e32 v138, v138
	v_mul_f32_e32 v131, 0xbfb8aa3b, v28
	v_mul_f32_e32 v139, 0xbfb8aa3b, v26
	v_mul_f32_e32 v140, 0xbfb8aa3b, v27
	v_exp_f32_e32 v131, v131
	v_mul_f32_e32 v133, v30, v133
	v_mul_f32_e32 v134, v31, v134
	v_mul_f32_e32 v135, v24, v135
	v_exp_f32_e32 v139, v139
	v_exp_f32_e32 v140, v140
	v_mul_f32_e32 v138, v25, v138
	v_cndmask_b32_e64 v133, v133, v30, s[38:39]
	v_cndmask_b32_e64 v134, v134, v31, s[38:39]
	v_cndmask_b32_e64 v135, v135, v24, s[38:39]
	v_cndmask_b32_e64 v138, v138, v25, s[38:39]
	v_cvt_pk_bf16_f32 v133, v133, v134
	v_cvt_pk_bf16_f32 v134, v135, v138
	v_mul_f32_e32 v135, 0xbfb8aa3b, v21
	v_exp_f32_e32 v138, v135
	v_add_f32_e32 v131, 1.0, v131
	v_add_f32_e32 v139, 1.0, v139
	v_add_f32_e32 v140, 1.0, v140
	v_rcp_f32_e32 v131, v131
	v_rcp_f32_e32 v139, v139
	v_rcp_f32_e32 v140, v140
	v_add_f32_e32 v138, 1.0, v138
	v_rcp_f32_e32 v138, v138
	v_mul_f32_e32 v131, v28, v131
	v_mul_f32_e32 v139, v26, v139
	v_mul_f32_e32 v140, v27, v140
	v_cndmask_b32_e64 v131, v131, v28, s[38:39]
	v_cndmask_b32_e64 v132, v132, v29, s[38:39]
	v_cndmask_b32_e64 v139, v139, v26, s[38:39]
	v_cndmask_b32_e64 v140, v140, v27, s[38:39]
	v_cvt_pk_bf16_f32 v132, v131, v132
	v_cvt_pk_bf16_f32 v135, v139, v140
	v_mul_f32_e32 v131, 0xbfb8aa3b, v20
	global_store_dwordx4 v[136:137], v[132:135], off
	v_mul_f32_e32 v139, 0xbfb8aa3b, v18
	v_mul_f32_e32 v140, 0xbfb8aa3b, v19
	v_mul_f32_e32 v132, v21, v138
	v_mul_f32_e32 v133, 0xbfb8aa3b, v22
	v_mul_f32_e32 v134, 0xbfb8aa3b, v23
	v_mul_f32_e32 v135, 0xbfb8aa3b, v16
	v_mul_f32_e32 v138, 0xbfb8aa3b, v17
	v_exp_f32_e32 v131, v131
	v_exp_f32_e32 v133, v133
	v_exp_f32_e32 v134, v134
	v_exp_f32_e32 v135, v135
	v_exp_f32_e32 v138, v138
	v_exp_f32_e32 v139, v139
	v_exp_f32_e32 v140, v140
	v_add_f32_e32 v131, 1.0, v131
	v_add_f32_e32 v133, 1.0, v133
	v_pk_add_f32 v[134:135], v[134:135], 1.0 op_sel_hi:[1,0]
	s_nop 0
	v_pk_add_f32 v[138:139], v[138:139], 1.0 op_sel_hi:[1,0]
	s_nop 0
	v_add_f32_e32 v140, 1.0, v140
	v_rcp_f32_e32 v131, v131
	v_rcp_f32_e32 v133, v133
	v_rcp_f32_e32 v134, v134
	v_rcp_f32_e32 v135, v135
	v_rcp_f32_e32 v138, v138
	v_rcp_f32_e32 v139, v139
	v_rcp_f32_e32 v140, v140
	v_mul_f32_e32 v131, v20, v131
	v_mul_f32_e32 v133, v22, v133
	v_mul_f32_e32 v134, v23, v134
	v_mul_f32_e32 v135, v16, v135
	v_mul_f32_e32 v138, v17, v138
	v_mul_f32_e32 v139, v18, v139
	v_mul_f32_e32 v140, v19, v140
	v_cndmask_b32_e64 v131, v131, v20, s[38:39]
	v_cndmask_b32_e64 v132, v132, v21, s[38:39]
	v_cndmask_b32_e64 v133, v133, v22, s[38:39]
	v_cndmask_b32_e64 v134, v134, v23, s[38:39]
	v_cndmask_b32_e64 v135, v135, v16, s[38:39]
	v_cndmask_b32_e64 v138, v138, v17, s[38:39]
	v_cndmask_b32_e64 v139, v139, v18, s[38:39]
	v_cndmask_b32_e64 v140, v140, v19, s[38:39]
	v_cvt_pk_bf16_f32 v132, v131, v132
	v_cvt_pk_bf16_f32 v133, v133, v134
	v_cvt_pk_bf16_f32 v134, v135, v138
	v_cvt_pk_bf16_f32 v135, v139, v140
	global_store_dwordx4 v[136:137], v[132:135], off offset:256
	v_add_u32_e32 v130, 0xb0, v130
	v_ashrrev_i32_e32 v131, 31, v130
	v_mul_f32_e32 v134, 0xbfb8aa3b, v12
	v_exp_f32_e32 v134, v134
	v_mul_f32_e32 v135, 0xbfb8aa3b, v13
	v_exp_f32_e32 v135, v135
	v_mul_lo_u32 v132, s40, v131
	v_mul_lo_u32 v133, s41, v130
	v_mad_u64_u32 v[130:131], s[10:11], s40, v130, 0
	v_add3_u32 v131, v131, v132, v133
	v_add_f32_e32 v132, 1.0, v134
	v_rcp_f32_e32 v134, v132
	v_add_f32_e32 v132, 1.0, v135
	v_rcp_f32_e32 v135, v132
	v_lshl_add_u64 v[132:133], v[130:131], 1, v[128:129]
	v_mul_f32_e32 v130, 0xbfb8aa3b, v14
	v_mul_f32_e32 v131, 0xbfb8aa3b, v15
	v_mul_f32_e32 v128, v12, v134
	v_mul_f32_e32 v129, v13, v135
	v_exp_f32_e32 v130, v130
	v_exp_f32_e32 v131, v131
	v_mul_f32_e32 v134, 0xbfb8aa3b, v8
	v_mul_f32_e32 v135, 0xbfb8aa3b, v9
	v_exp_f32_e32 v134, v134
	v_exp_f32_e32 v135, v135
	v_pk_add_f32 v[130:131], v[130:131], 1.0 op_sel_hi:[1,0]
	s_nop 0
	v_rcp_f32_e32 v130, v130
	v_rcp_f32_e32 v131, v131
	v_pk_add_f32 v[134:135], v[134:135], 1.0 op_sel_hi:[1,0]
	s_nop 0
	v_rcp_f32_e32 v134, v134
	v_rcp_f32_e32 v135, v135
	v_mul_f32_e32 v130, v14, v130
	v_mul_f32_e32 v131, v15, v131
	v_mul_f32_e32 v136, 0xbfb8aa3b, v10
	v_mul_f32_e32 v137, 0xbfb8aa3b, v11
	v_cndmask_b32_e64 v128, v128, v12, s[38:39]
	v_cndmask_b32_e64 v129, v129, v13, s[38:39]
	v_cndmask_b32_e64 v130, v130, v14, s[38:39]
	v_cndmask_b32_e64 v131, v131, v15, s[38:39]
	v_mul_f32_e32 v134, v8, v134
	v_exp_f32_e32 v136, v136
	v_exp_f32_e32 v137, v137
	v_mul_f32_e32 v135, v9, v135
	v_cndmask_b32_e64 v134, v134, v8, s[38:39]
	v_cndmask_b32_e64 v135, v135, v9, s[38:39]
	v_cvt_pk_bf16_f32 v128, v128, v129
	v_cvt_pk_bf16_f32 v129, v130, v131
	v_mul_f32_e32 v131, 0xbfb8aa3b, v4
	v_cvt_pk_bf16_f32 v130, v134, v135
	v_exp_f32_e32 v134, v131
	v_mul_f32_e32 v131, 0xbfb8aa3b, v5
	v_exp_f32_e32 v135, v131
	v_pk_add_f32 v[136:137], v[136:137], 1.0 op_sel_hi:[1,0]
	s_nop 0
	v_rcp_f32_e32 v136, v136
	v_rcp_f32_e32 v137, v137
	v_pk_add_f32 v[134:135], v[134:135], 1.0 op_sel_hi:[1,0]
	s_nop 0
	v_rcp_f32_e32 v134, v134
	v_rcp_f32_e32 v135, v135
	v_mul_f32_e32 v136, v10, v136
	v_mul_f32_e32 v137, v11, v137
	v_cndmask_b32_e64 v136, v136, v10, s[38:39]
	v_cndmask_b32_e64 v137, v137, v11, s[38:39]
	v_cvt_pk_bf16_f32 v131, v136, v137
	global_store_dwordx4 v[132:133], v[128:131], off
	v_mul_f32_e32 v136, 0xbfb8aa3b, v2
	v_mul_f32_e32 v137, 0xbfb8aa3b, v3
	v_mul_f32_e32 v128, v4, v134
	v_mul_f32_e32 v129, v5, v135
	v_mul_f32_e32 v130, 0xbfb8aa3b, v6
	v_mul_f32_e32 v131, 0xbfb8aa3b, v7
	v_mul_f32_e32 v134, 0xbfb8aa3b, v0
	v_mul_f32_e32 v135, 0xbfb8aa3b, v1
	v_exp_f32_e32 v130, v130
	v_exp_f32_e32 v131, v131
	v_exp_f32_e32 v134, v134
	v_exp_f32_e32 v135, v135
	v_exp_f32_e32 v136, v136
	v_exp_f32_e32 v137, v137
	v_pk_add_f32 v[130:131], v[130:131], 1.0 op_sel_hi:[1,0]
	s_nop 0
	v_pk_add_f32 v[134:135], v[134:135], 1.0 op_sel_hi:[1,0]
	s_nop 0
	v_pk_add_f32 v[136:137], v[136:137], 1.0 op_sel_hi:[1,0]
	s_nop 0
	v_rcp_f32_e32 v130, v130
	v_rcp_f32_e32 v131, v131
	v_rcp_f32_e32 v134, v134
	v_rcp_f32_e32 v135, v135
	v_rcp_f32_e32 v136, v136
	v_rcp_f32_e32 v137, v137
	v_mul_f32_e32 v130, v6, v130
	v_mul_f32_e32 v131, v7, v131
	v_mul_f32_e32 v134, v0, v134
	v_mul_f32_e32 v135, v1, v135
	v_mul_f32_e32 v136, v2, v136
	v_mul_f32_e32 v137, v3, v137
	v_cndmask_b32_e64 v128, v128, v4, s[38:39]
	v_cndmask_b32_e64 v129, v129, v5, s[38:39]
	v_cndmask_b32_e64 v130, v130, v6, s[38:39]
	v_cndmask_b32_e64 v131, v131, v7, s[38:39]
	v_cndmask_b32_e64 v134, v134, v0, s[38:39]
	v_cndmask_b32_e64 v135, v135, v1, s[38:39]
	v_cndmask_b32_e64 v136, v136, v2, s[38:39]
	v_cndmask_b32_e64 v137, v137, v3, s[38:39]
	v_cvt_pk_bf16_f32 v128, v128, v129
	v_cvt_pk_bf16_f32 v129, v130, v131
	v_cvt_pk_bf16_f32 v130, v134, v135
	v_cvt_pk_bf16_f32 v131, v136, v137
	global_store_dwordx4 v[132:133], v[128:131], off offset:256
